# prologue: remaining input loads (read once) also marked nt
# speedup vs baseline: 1.0006x; 1.0006x over previous
.LBB0_27:
	s_cmpk_gt_i32 s74, 0x17f
	s_mov_b64 s[12:13], -1
	s_cbranch_scc0 .LBB0_36
	s_cmpk_eq_i32 s74, 0x1c0
	s_cbranch_scc1 .LBB0_43
	s_and_saveexec_b64 s[28:29], s[10:11]
	s_cbranch_execz .LBB0_42
	s_load_dwordx16 s[36:51], s[0:1], 0xc0
	s_add_i32 s22, s74, 0xfffffe80
	s_lshl_b64 s[12:13], s[22:23], 2
	v_lshl_add_u32 v0, s22, 6, v42
	v_ashrrev_i32_e32 v1, 31, v0
	s_waitcnt lgkmcnt(0)
	s_add_u32 s12, s42, s12
	s_addc_u32 s13, s43, s13
	global_load_dword v4, v53, s[12:13] nt
	v_lshlrev_b64 v[0:1], 2, v[0:1]
	v_lshl_add_u64 v[2:3], s[40:41], 0, v[0:1]
	global_load_dword v2, v[2:3], off nt
	v_lshl_add_u64 v[0:1], s[38:39], 0, v[0:1]
	global_load_dword v3, v[0:1], off nt
	s_waitcnt vmcnt(2)
	v_mul_f32_e32 v0, 0x3fb8aa3b, v4
	v_fma_f32 v1, v4, s61, -v0
	v_rndne_f32_e32 v5, v0
	v_fmac_f32_e32 v1, 0x32a5705f, v4
	v_sub_f32_e32 v0, v0, v5
	v_add_f32_e32 v0, v0, v1
	v_cvt_i32_f32_e32 v5, v5
	v_exp_f32_e32 v0, v0
	v_cmp_ngt_f32_e32 vcc, s62, v4
	v_ldexp_f32 v0, v0, v5
	s_nop 0
	v_cndmask_b32_e32 v0, 0, v0, vcc
	v_cmp_nlt_f32_e32 vcc, s63, v4
	s_nop 1
	v_cndmask_b32_e32 v4, v81, v0, vcc
	s_waitcnt vmcnt(1)
	v_mul_f32_e32 v0, v2, v4
	v_and_b32_e32 v1, 0x7fffffff, v0
	v_lshrrev_b32_e32 v5, 23, v1
	v_and_b32_e32 v6, 0x7fffff, v1
	v_cmp_nlt_f32_e64 s[30:31], |v0|, s64
	v_add_u32_e32 v8, 0xffffff88, v5
	v_or_b32_e32 v7, 0x800000, v6
	s_and_saveexec_b64 s[12:13], s[30:31]
	s_xor_b64 s[34:35], exec, s[12:13]
	s_cbranch_execz .LBB0_32
	v_mad_u64_u32 v[10:11], s[16:17], v7, s65, 0
	v_mov_b32_e32 v52, v11
	v_mad_u64_u32 v[12:13], s[16:17], v7, s66, v[52:53]
	v_mov_b32_e32 v52, v13
	v_mad_u64_u32 v[14:15], s[16:17], v7, s67, v[52:53]
	v_cmp_lt_u32_e32 vcc, 63, v8
	v_mov_b32_e32 v52, v15
	v_mad_u64_u32 v[16:17], s[16:17], v7, s68, v[52:53]
	v_cndmask_b32_e32 v5, 0, v83, vcc
	v_add_u32_e32 v5, v5, v8
	v_mov_b32_e32 v52, v17
	v_cmp_lt_u32_e64 s[12:13], 31, v5
	v_mad_u64_u32 v[18:19], s[16:17], v7, s69, v[52:53]
	s_nop 0
	v_cndmask_b32_e64 v6, 0, v85, s[12:13]
	v_mov_b32_e32 v52, v19
	v_add_u32_e32 v5, v6, v5
	v_mad_u64_u32 v[20:21], s[16:17], v7, s70, v[52:53]
	v_cmp_lt_u32_e64 s[14:15], 31, v5
	v_mov_b32_e32 v52, v21
	v_mad_u64_u32 v[22:23], s[16:17], v7, s71, v[52:53]
	v_cndmask_b32_e64 v6, 0, v85, s[14:15]
	v_add_u32_e32 v5, v6, v5
	v_cndmask_b32_e32 v6, v20, v16, vcc
	v_cndmask_b32_e32 v9, v22, v18, vcc
	v_cndmask_b32_e32 v13, v23, v20, vcc
	v_cndmask_b32_e64 v11, v9, v6, s[12:13]
	v_cndmask_b32_e64 v9, v13, v9, s[12:13]
	v_cndmask_b32_e32 v13, v18, v14, vcc
	v_cndmask_b32_e64 v6, v6, v13, s[12:13]
	v_cndmask_b32_e64 v9, v9, v11, s[14:15]
	v_cndmask_b32_e64 v11, v11, v6, s[14:15]
	v_sub_u32_e32 v15, 32, v5
	v_alignbit_b32 v17, v9, v11, v15
	v_cmp_eq_u32_e64 s[16:17], 0, v5
	v_cndmask_b32_e32 v10, v14, v10, vcc
	s_nop 0
	v_cndmask_b32_e64 v5, v17, v9, s[16:17]
	v_cndmask_b32_e32 v9, v16, v12, vcc
	v_cndmask_b32_e64 v12, v13, v9, s[12:13]
	v_cndmask_b32_e64 v6, v6, v12, s[14:15]
	v_alignbit_b32 v13, v11, v6, v15
	v_cndmask_b32_e64 v9, v9, v10, s[12:13]
	v_cndmask_b32_e64 v11, v13, v11, s[16:17]
	v_bfe_u32 v17, v5, 29, 1
	v_cndmask_b32_e64 v9, v12, v9, s[14:15]
	v_alignbit_b32 v13, v5, v11, 30
	v_sub_u32_e32 v18, 0, v17
	v_alignbit_b32 v10, v6, v9, v15
	v_xor_b32_e32 v13, v13, v18
	v_cndmask_b32_e64 v6, v10, v6, s[16:17]
	v_alignbit_b32 v10, v11, v6, 30
	v_ffbh_u32_e32 v11, v13
	v_min_u32_e32 v11, 32, v11
	v_alignbit_b32 v6, v6, v9, 30
	v_xor_b32_e32 v10, v10, v18
	v_sub_u32_e32 v12, 31, v11
	v_xor_b32_e32 v6, v6, v18
	v_alignbit_b32 v13, v13, v10, v12
	v_alignbit_b32 v6, v10, v6, v12
	v_alignbit_b32 v9, v13, v6, 9
	v_ffbh_u32_e32 v10, v9
	v_min_u32_e32 v10, 32, v10
	v_lshrrev_b32_e32 v16, 29, v5
	v_not_b32_e32 v12, v10
	v_alignbit_b32 v6, v9, v6, v12
	v_lshlrev_b32_e32 v9, 31, v16
	v_or_b32_e32 v12, 0x33000000, v9
	v_add_lshl_u32 v10, v10, v11, 23
	v_lshrrev_b32_e32 v6, 9, v6
	v_sub_u32_e32 v10, v12, v10
	v_or_b32_e32 v9, 0.5, v9
	v_lshlrev_b32_e32 v11, 23, v11
	v_or_b32_e32 v6, v10, v6
	v_lshrrev_b32_e32 v10, 9, v13
	v_sub_u32_e32 v9, v9, v11
	v_or_b32_e32 v9, v10, v9
	v_mul_f32_e32 v10, 0x3fc90fda, v9
	v_fma_f32 v11, v9, s52, -v10
	v_fmac_f32_e32 v11, 0x33a22168, v9
	v_fmac_f32_e32 v11, 0x3fc90fda, v6
	v_lshrrev_b32_e32 v5, 30, v5
	v_add_f32_e32 v6, v10, v11
	v_add_u32_e32 v5, v17, v5

.LBB0_40:
	v_lshl_add_u64 v[20:21], v[10:11], 0, s[12:13]
	v_lshl_add_u64 v[16:17], v[12:13], 0, s[12:13]
	v_lshl_add_u64 v[24:25], v[4:5], 0, s[12:13]
	v_lshl_add_u64 v[26:27], v[6:7], 0, s[12:13]
	global_load_dwordx4 v[16:19], v[16:17], off nt
	s_nop 0
	global_load_dword v34, v[24:25], off nt
	global_load_dword v35, v[26:27], off nt
	global_load_dword v36, v[26:27], off offset:256 nt
	global_load_dword v37, v[24:25], off offset:256 nt
	global_load_dword v38, v[24:25], off offset:512 nt
	global_load_dword v39, v[26:27], off offset:512 nt
	s_nop 0
	global_load_dwordx4 v[20:23], v[20:21], off nt
	s_nop 0
	global_load_dword v40, v[24:25], off offset:768 nt
	global_load_dword v41, v[26:27], off offset:768 nt
	v_add_u32_e32 v29, s16, v44
	v_lshl_add_u64 v[26:27], v[8:9], 0, s[12:13]
	s_addk_i32 s16, 0x200
	s_mov_b32 s17, 0x8b000
	v_add_u32_e32 v28, 0x80, v29
	v_add_u32_e32 v30, 0x100, v29
	v_add_u32_e32 v32, 0x180, v29
	v_lshl_add_u64 v[24:25], v[2:3], 0, s[12:13]
	v_lshl_add_u64 v[12:13], v[12:13], 0, 16
	v_lshl_add_u64 v[10:11], v[10:11], 0, 16
	v_lshl_add_u64 v[8:9], v[8:9], 0, s[26:27]
	v_lshl_add_u64 v[6:7], v[6:7], 0, s[26:27]
	v_lshl_add_u64 v[4:5], v[4:5], 0, s[26:27]
	v_lshl_add_u64 v[2:3], v[2:3], 0, 8
	v_add_co_u32_e32 v26, vcc, s17, v26
	s_cmpk_eq_i32 s16, 0x800
	v_ashrrev_i32_e32 v29, 31, v28
	v_ashrrev_i32_e32 v31, 31, v30
	v_ashrrev_i32_e32 v33, 31, v32
	v_addc_co_u32_e32 v27, vcc, 0, v27, vcc
	v_lshl_add_u64 v[28:29], v[28:29], 1, s[14:15]
	v_lshl_add_u64 v[30:31], v[30:31], 1, s[14:15]
	v_lshl_add_u64 v[32:33], v[32:33], 1, s[14:15]
	s_waitcnt vmcnt(9)
	v_mul_f32_e32 v52, v15, v16
	v_mul_f32_e32 v16, v14, v16
	s_waitcnt vmcnt(7)
	v_cvt_pk_bf16_f32 v34, v34, -v35
	v_mul_f32_e32 v35, v15, v17
	v_mul_f32_e32 v17, v14, v17
	s_waitcnt vmcnt(5)
	v_cvt_pk_bf16_f32 v36, v37, -v36
	v_mul_f32_e32 v37, v15, v18
	v_mul_f32_e32 v18, v14, v18
	s_waitcnt vmcnt(3)
	v_cvt_pk_bf16_f32 v38, v38, -v39
	v_mul_f32_e32 v39, v15, v19
	v_mul_f32_e32 v19, v14, v19
	s_waitcnt vmcnt(0)
	v_cvt_pk_bf16_f32 v40, v40, -v41
	v_fma_f32 v41, v14, v20, -v52
	v_fmac_f32_e32 v16, v15, v20
	v_fma_f32 v20, v14, v21, -v35
	v_fmac_f32_e32 v17, v15, v21
	v_fma_f32 v21, v14, v22, -v37
	v_fmac_f32_e32 v18, v15, v22
	v_fma_f32 v22, v14, v23, -v39
	v_fmac_f32_e32 v19, v15, v23
	v_cvt_pk_bf16_f32 v23, v41, s0
	v_cvt_pk_bf16_f32 v16, v16, s0
	v_cvt_pk_bf16_f32 v20, v20, s0
	v_cvt_pk_bf16_f32 v17, v17, s0
	v_cvt_pk_bf16_f32 v21, v21, s0
	v_cvt_pk_bf16_f32 v18, v18, s0
	v_cvt_pk_bf16_f32 v22, v22, s0
	v_cvt_pk_bf16_f32 v19, v19, s0
	global_store_short v[24:25], v23, off offset:-32
	global_store_short v[24:25], v16, off
	global_store_dword v[26:27], v34, off offset:1792
	global_store_short v[24:25], v20, off offset:-30
	global_store_short v[24:25], v17, off offset:2
	global_store_dword v[28:29], v36, off
	global_store_short v[24:25], v21, off offset:-28
	global_store_short v[24:25], v18, off offset:4
	global_store_dword v[30:31], v38, off
	global_store_short v[24:25], v22, off offset:-26
	global_store_short v[24:25], v19, off offset:6
	global_store_dword v[32:33], v40, off
	s_cbranch_scc0 .LBB0_40
	s_lshl_b64 s[12:13], s[22:23], 9
	v_lshl_add_u64 v[2:3], v[56:57], 0, s[12:13]
	global_store_dwordx2 v[2:3], v[0:1], off

.LBB0_61:
	s_or_b64 exec, exec, s[16:17]
	global_load_dword v0, v[0:1], off nt
	s_movk_i32 s16, 0x11ff
	v_add_u32_e32 v4, 0x200, v3
	v_cmp_lt_i32_e32 vcc, s16, v3
	s_or_b64 s[14:15], vcc, s[14:15]
	v_mov_b32_e32 v3, v4
	s_waitcnt vmcnt(0)
	v_mul_f32_e32 v1, 0xbfb8aa3b, v0
	v_exp_f32_e32 v1, v1
	s_nop 0
	v_add_f32_e32 v1, 1.0, v1
	v_rcp_f32_e32 v1, v1
	s_nop 0
	v_mul_f32_e32 v0, v0, v1
	ds_write_b32 v2, v0
	v_add_u32_e32 v2, 0x800, v2
	s_andn2_b64 exec, exec, s[14:15]
	s_cbranch_execz .LBB0_66

.LBB0_67:
	v_lshl_add_u64 v[16:17], v[74:75], 0, s[16:17]
	v_add_co_u32_e32 v96, vcc, s73, v16
	s_mov_b32 s13, 0xc000
	s_nop 0
	v_addc_co_u32_e32 v97, vcc, 0, v17, vcc
	v_add_co_u32_e32 v98, vcc, s13, v16
	s_mov_b32 s13, 0x12000
	s_nop 0
	v_addc_co_u32_e32 v99, vcc, 0, v17, vcc
	v_add_co_u32_e32 v100, vcc, s13, v16
	s_mov_b32 s13, 0x18000
	s_nop 0
	v_addc_co_u32_e32 v101, vcc, 0, v17, vcc
	ds_read_b128 v[34:37], v91
	ds_read_b128 v[12:15], v91 offset:16
	ds_read_b128 v[4:7], v91 offset:32
	ds_read_b128 v[0:3], v91 offset:48
	ds_read_b128 v[8:11], v91 offset:4096
	ds_read_b128 v[18:21], v91 offset:4112
	ds_read_b128 v[38:41], v91 offset:8192
	ds_read_b128 v[26:29], v91 offset:8208
	ds_read_b128 v[92:95], v91 offset:12288
	ds_read_b128 v[22:25], v91 offset:12304
	global_load_dword v52, v[16:17], off nt
	v_add_co_u32_e32 v102, vcc, s13, v16
	s_mov_b32 s13, 0x1e000
	s_nop 0
	v_addc_co_u32_e32 v103, vcc, 0, v17, vcc
	v_add_co_u32_e32 v104, vcc, s13, v16
	s_mov_b32 s13, 0x24000
	s_nop 0
	v_addc_co_u32_e32 v105, vcc, 0, v17, vcc
	v_add_co_u32_e32 v106, vcc, s13, v16
	s_mov_b32 s13, 0x2a000
	s_nop 0
	v_addc_co_u32_e32 v107, vcc, 0, v17, vcc
	s_waitcnt lgkmcnt(3)
	v_mov_b32_e32 v110, v38
	v_add_co_u32_e32 v38, vcc, s13, v16
	v_mov_b32_e32 v108, v34
	v_mov_b32_e32 v34, v36
	s_waitcnt lgkmcnt(1)
	v_mov_b32_e32 v111, v92
	v_mov_b32_e32 v92, v39
	v_addc_co_u32_e32 v39, vcc, 0, v17, vcc
	global_load_dword v76, v[96:97], off nt
	global_load_dword v78, v[98:99], off nt
	global_load_dword v80, v[100:101], off nt
	s_nop 0
	global_load_dword v96, v[102:103], off nt
	global_load_dword v98, v[104:105], off nt
	global_load_dword v36, v[106:107], off nt
	global_load_dword v90, v[38:39], off nt
	s_mov_b32 s13, 0x30000
	v_mov_b32_e32 v112, v40
	v_mov_b32_e32 v113, v94
	v_mov_b32_e32 v94, v41
	ds_read_b128 v[38:41], v91 offset:16384
	v_mov_b32_e32 v109, v8
	v_mov_b32_e32 v8, v35
	v_mov_b32_e32 v35, v10
	v_mov_b32_e32 v10, v37
	s_add_u32 s16, s16, 0x60000
	s_addc_u32 s17, s17, 0
	s_cmp_eq_u32 s16, 0x180000
	s_waitcnt vmcnt(7)
	v_pk_fma_f32 v[30:31], v[52:53], v[110:111], v[30:31] op_sel_hi:[0,1,1]
	v_pk_fma_f32 v[32:33], v[52:53], v[108:109], v[32:33] op_sel_hi:[0,1,1]
	s_waitcnt vmcnt(6)
	v_pk_fma_f32 v[30:31], v[76:77], v[92:93], v[30:31] op_sel_hi:[0,1,1]
	v_add_co_u32_e32 v92, vcc, s13, v16
	s_waitcnt vmcnt(5)
	v_pk_fma_f32 v[30:31], v[78:79], v[112:113], v[30:31] op_sel_hi:[0,1,1]
	v_addc_co_u32_e32 v93, vcc, 0, v17, vcc
	s_mov_b32 s13, 0x36000
	s_waitcnt vmcnt(4)
	v_pk_fma_f32 v[30:31], v[80:81], v[94:95], v[30:31] op_sel_hi:[0,1,1]
	v_add_co_u32_e32 v94, vcc, s13, v16
	s_mov_b32 s13, 0x3c000
	s_nop 0
	v_addc_co_u32_e32 v95, vcc, 0, v17, vcc
	v_add_co_u32_e32 v102, vcc, s13, v16
	s_mov_b32 s13, 0x42000
	s_nop 0
	v_addc_co_u32_e32 v103, vcc, 0, v17, vcc
	v_pk_fma_f32 v[8:9], v[76:77], v[8:9], v[32:33] op_sel_hi:[0,1,1]
	v_add_co_u32_e32 v104, vcc, s13, v16
	v_pk_fma_f32 v[8:9], v[78:79], v[34:35], v[8:9] op_sel_hi:[0,1,1]
	s_nop 0
	v_addc_co_u32_e32 v105, vcc, 0, v17, vcc
	s_mov_b32 s13, 0x48000
	v_pk_fma_f32 v[100:101], v[80:81], v[10:11], v[8:9] op_sel_hi:[0,1,1]
	ds_read_b128 v[8:11], v91 offset:4128
	s_waitcnt lgkmcnt(1)
	v_fmac_f32_e32 v89, v52, v38
	v_add_co_u32_e32 v38, vcc, s13, v16
	v_fmac_f32_e32 v89, v76, v39
	s_nop 0
	v_addc_co_u32_e32 v39, vcc, 0, v17, vcc
	s_mov_b32 s13, 0x4e000
	v_add_co_u32_e32 v106, vcc, s13, v16
	s_mov_b32 s13, 0x54000
	s_nop 0
	v_addc_co_u32_e32 v107, vcc, 0, v17, vcc
	v_fmac_f32_e32 v89, v78, v40
	v_add_co_u32_e32 v40, vcc, s13, v16
	v_fmac_f32_e32 v89, v80, v41
	s_nop 0
	v_addc_co_u32_e32 v41, vcc, 0, v17, vcc
	s_mov_b32 s13, 0x5a000
	v_add_co_u32_e32 v16, vcc, s13, v16
	ds_read_b128 v[32:35], v91 offset:16400
	s_nop 0
	v_addc_co_u32_e32 v17, vcc, 0, v17, vcc
	global_load_dword v88, v[92:93], off nt
	global_load_dword v86, v[94:95], off nt
	global_load_dword v84, v[102:103], off nt
	global_load_dword v82, v[104:105], off nt
	global_load_dword v80, v[38:39], off nt
	global_load_dword v78, v[106:107], off nt
	global_load_dword v76, v[40:41], off nt
	global_load_dword v52, v[16:17], off nt
	v_mov_b32_e32 v16, v12
	v_mov_b32_e32 v17, v18
	v_mov_b32_e32 v18, v13
	v_mov_b32_e32 v12, v26
	v_mov_b32_e32 v13, v22
	v_mov_b32_e32 v22, v27
	s_waitcnt vmcnt(11)
	v_pk_fma_f32 v[16:17], v[96:97], v[16:17], v[100:101] op_sel_hi:[0,1,1]
	v_pk_fma_f32 v[30:31], v[96:97], v[12:13], v[30:31] op_sel_hi:[0,1,1]
	v_mov_b32_e32 v38, v14
	v_mov_b32_e32 v39, v20
	v_mov_b32_e32 v40, v28
	v_mov_b32_e32 v41, v24
	s_waitcnt vmcnt(10)
	v_pk_fma_f32 v[92:93], v[98:99], v[18:19], v[16:17] op_sel_hi:[0,1,1]
	v_pk_fma_f32 v[22:23], v[98:99], v[22:23], v[30:31] op_sel_hi:[0,1,1]
	v_mov_b32_e32 v20, v15
	v_mov_b32_e32 v24, v29
	ds_read_b128 v[26:29], v91 offset:8224
	ds_read_b128 v[12:15], v91 offset:12320
	s_waitcnt lgkmcnt(2)
	v_fmac_f32_e32 v89, v96, v32
	s_waitcnt vmcnt(9)
	v_pk_fma_f32 v[38:39], v[36:37], v[38:39], v[92:93] op_sel_hi:[0,1,1]
	v_pk_fma_f32 v[22:23], v[36:37], v[40:41], v[22:23] op_sel_hi:[0,1,1]
	v_fmac_f32_e32 v89, v98, v33
	ds_read_b128 v[16:19], v91 offset:16416
	ds_read_b128 v[30:33], v91 offset:4144
	s_waitcnt vmcnt(8)
	v_pk_fma_f32 v[92:93], v[90:91], v[20:21], v[38:39] op_sel_hi:[0,1,1]
	ds_read_b128 v[38:41], v91 offset:8240
	v_pk_fma_f32 v[24:25], v[90:91], v[24:25], v[22:23] op_sel_hi:[0,1,1]
	ds_read_b128 v[20:23], v91 offset:12336
	v_fmac_f32_e32 v89, v36, v34
	v_fmac_f32_e32 v89, v90, v35
	ds_read_b128 v[34:37], v91 offset:16432
	v_mov_b32_e32 v94, v4
	v_mov_b32_e32 v95, v8
	v_mov_b32_e32 v8, v5
	v_mov_b32_e32 v4, v6
	v_mov_b32_e32 v5, v10
	v_mov_b32_e32 v10, v7
	s_waitcnt lgkmcnt(6)
	v_mov_b32_e32 v6, v26
	s_waitcnt lgkmcnt(5)
	v_mov_b32_e32 v7, v12
	v_mov_b32_e32 v12, v27
	v_mov_b32_e32 v26, v28
	v_mov_b32_e32 v27, v14
	v_mov_b32_e32 v14, v29
	v_mov_b32_e32 v28, v0
	s_waitcnt lgkmcnt(3)
	v_mov_b32_e32 v29, v30
	v_mov_b32_e32 v30, v1
	v_mov_b32_e32 v0, v2
	v_mov_b32_e32 v1, v32
	v_mov_b32_e32 v32, v3
	s_waitcnt lgkmcnt(2)
	v_mov_b32_e32 v2, v38
	s_waitcnt lgkmcnt(1)
	v_mov_b32_e32 v3, v20
	v_mov_b32_e32 v20, v39
	v_mov_b32_e32 v38, v40
	v_mov_b32_e32 v39, v22
	v_mov_b32_e32 v22, v41
	v_add_u32_e32 v91, 64, v91
	s_waitcnt vmcnt(7)
	v_pk_fma_f32 v[40:41], v[88:89], v[94:95], v[92:93] op_sel_hi:[0,1,1]
	v_pk_fma_f32 v[6:7], v[88:89], v[6:7], v[24:25] op_sel_hi:[0,1,1]
	v_fmac_f32_e32 v89, v88, v16
	s_waitcnt vmcnt(6)
	v_pk_fma_f32 v[8:9], v[86:87], v[8:9], v[40:41] op_sel_hi:[0,1,1]
	v_pk_fma_f32 v[6:7], v[86:87], v[12:13], v[6:7] op_sel_hi:[0,1,1]
	v_fmac_f32_e32 v89, v86, v17
	s_waitcnt vmcnt(5)
	v_pk_fma_f32 v[4:5], v[84:85], v[4:5], v[8:9] op_sel_hi:[0,1,1]
	v_pk_fma_f32 v[6:7], v[84:85], v[26:27], v[6:7] op_sel_hi:[0,1,1]
	v_fmac_f32_e32 v89, v84, v18
	s_waitcnt vmcnt(4)
	v_pk_fma_f32 v[4:5], v[82:83], v[10:11], v[4:5] op_sel_hi:[0,1,1]
	v_pk_fma_f32 v[6:7], v[82:83], v[14:15], v[6:7] op_sel_hi:[0,1,1]
	v_fmac_f32_e32 v89, v82, v19
	s_waitcnt vmcnt(3)
	v_pk_fma_f32 v[4:5], v[80:81], v[28:29], v[4:5] op_sel_hi:[0,1,1]
	v_pk_fma_f32 v[2:3], v[80:81], v[2:3], v[6:7] op_sel_hi:[0,1,1]
	s_waitcnt lgkmcnt(0)
	v_fmac_f32_e32 v89, v80, v34
	s_waitcnt vmcnt(2)
	v_pk_fma_f32 v[4:5], v[78:79], v[30:31], v[4:5] op_sel_hi:[0,1,1]
	v_pk_fma_f32 v[2:3], v[78:79], v[20:21], v[2:3] op_sel_hi:[0,1,1]
	v_fmac_f32_e32 v89, v78, v35
	s_waitcnt vmcnt(1)
	v_pk_fma_f32 v[0:1], v[76:77], v[0:1], v[4:5] op_sel_hi:[0,1,1]
	v_pk_fma_f32 v[2:3], v[76:77], v[38:39], v[2:3] op_sel_hi:[0,1,1]
	v_fmac_f32_e32 v89, v76, v36
	s_waitcnt vmcnt(0)
	v_pk_fma_f32 v[32:33], v[52:53], v[32:33], v[0:1] op_sel_hi:[0,1,1]
	v_pk_fma_f32 v[30:31], v[52:53], v[22:23], v[2:3] op_sel_hi:[0,1,1]
	v_fmac_f32_e32 v89, v52, v37
	s_cbranch_scc0 .LBB0_67
	v_add_u32_e32 v0, 0x5000, v54
	ds_write2_b32 v0, v32, v33 offset1:32
	ds_write2_b32 v0, v30, v31 offset0:64 offset1:96
	ds_write_b32 v54, v89 offset:20992
	s_waitcnt lgkmcnt(0)
	s_barrier
	s_and_saveexec_b64 s[16:17], s[8:9]
	s_cbranch_execz .LBB0_25
	s_load_dwordx16 s[36:51], s[0:1], 0x40
	v_or_b32_e32 v0, s14, v46
	s_mul_i32 s13, s12, 0x1800
	v_add_u32_e32 v2, s13, v0
	v_ashrrev_i32_e32 v3, 31, v2
	s_waitcnt lgkmcnt(0)
	v_lshl_add_u64 v[2:3], v[2:3], 2, s[50:51]
	global_load_dword v22, v[2:3], off nt
	v_add_u32_e32 v1, 0x5000, v79
	v_add_u32_e32 v8, 0x5400, v79
	v_add_u32_e32 v10, 0x5a00, v79
	v_add_u32_e32 v12, 0x5e00, v79
	v_add_u32_e32 v14, 0x6400, v79
	v_add_u32_e32 v16, 0x6800, v79
	v_add_u32_e32 v18, 0x6e00, v79
	v_add_u32_e32 v20, 0x7200, v79
	v_mad_i64_i32 v[2:3], s[12:13], s12, 5, v[48:49]
	v_mov_b64_e32 v[4:5], s[18:19]
	ds_read2_b32 v[6:7], v1 offset1:160
	ds_read2_b32 v[8:9], v8 offset0:64 offset1:224
	ds_read2_b32 v[10:11], v10 offset1:160
	ds_read2_b32 v[12:13], v12 offset0:64 offset1:224
	ds_read2_b32 v[14:15], v14 offset1:160
	ds_read2_b32 v[16:17], v16 offset0:64 offset1:224
	ds_read2_b32 v[18:19], v18 offset1:160
	ds_read2_b32 v[20:21], v20 offset0:64 offset1:224
	v_mad_u64_u32 v[4:5], s[12:13], v2, s73, v[4:5]
	s_waitcnt lgkmcnt(7)
	v_add_f32_e32 v2, 0, v6
	v_add_f32_e32 v2, v2, v7
	s_waitcnt lgkmcnt(6)
	v_add_f32_e32 v2, v2, v8
	v_add_f32_e32 v2, v2, v9
	s_waitcnt lgkmcnt(5)
	v_add_f32_e32 v2, v2, v10
	v_add_f32_e32 v2, v2, v11
	s_waitcnt lgkmcnt(4)
	v_add_f32_e32 v2, v2, v12
	v_add_f32_e32 v2, v2, v13
	s_waitcnt lgkmcnt(3)
	v_add_f32_e32 v2, v2, v14
	v_add_f32_e32 v2, v2, v15
	s_waitcnt lgkmcnt(2)
	v_add_f32_e32 v2, v2, v16
	v_add_f32_e32 v2, v2, v17
	s_waitcnt lgkmcnt(1)
	v_add_f32_e32 v2, v2, v18
	v_add_f32_e32 v2, v2, v19
	s_waitcnt lgkmcnt(0)
	v_add_f32_e32 v2, v2, v20
	v_ashrrev_i32_e32 v1, 31, v0
	v_mad_i32_i24 v5, v3, s73, v5
	v_add_f32_e32 v2, v2, v21
	v_lshl_add_u64 v[0:1], v[0:1], 2, v[4:5]
	s_waitcnt vmcnt(0)
	v_add_f32_e32 v2, v2, v22
	global_store_dword v[0:1], v2, off
	s_branch .LBB0_25
